# sample memory attention score stage: the 16 per-slot cross-lane reductions (5 dependent ds_bpermute hops each) are issued level by level for all 16 sums instead of one chain after the other
# speedup vs baseline: 1.0173x; 1.0102x over previous
.LBB0_556:
	v_mov_b32_e32 v132, v208
	v_readlane_b32 s38, v254, 35
	v_and_b32_e32 v133, 31, v132
	v_lshlrev_b32_e32 v2, 3, v133
	v_readlane_b32 s39, v254, 36
	v_bfe_u32 v146, v132, 5, 1
	s_waitcnt vmcnt(0)
	v_or_b32_e32 v4, s3, v146
	s_waitcnt vmcnt(26)
	v_ashrrev_i32_e32 v5, 31, v4
	s_waitcnt vmcnt(0)
	v_lshlrev_b64 v[80:81], 9, v[4:5]
	v_lshl_add_u64 v[4:5], s[70:71], 0, v[80:81]
	global_load_dwordx2 v[138:139], v2, s[38:39]
	v_readlane_b32 s38, v254, 37
	v_readlane_b32 s39, v254, 38
	v_lshlrev_b64 v[4:5], 2, v[4:5]
	s_waitcnt vmcnt(0)
	v_lshlrev_b32_e32 v83, 16, v138
	s_nop 1
	global_load_dwordx2 v[134:135], v2, s[38:39]
	v_readlane_b32 s38, v253, 11
	v_readlane_b32 s39, v253, 12
	s_load_dwordx4 s[40:43], s[38:39], 0x10
	v_lshlrev_b32_e32 v2, 4, v133
	v_lshlrev_b32_e32 v82, 16, v139
	s_waitcnt lgkmcnt(0)
	v_lshl_add_u64 v[6:7], s[40:41], 0, v[4:5]
	v_lshl_add_u64 v[32:33], s[42:43], 0, v[4:5]
	v_lshl_add_u64 v[4:5], v[6:7], 0, v[2:3]
	v_add_co_u32_e32 v6, vcc, s91, v4
	s_movk_i32 s1, 0x6000
	s_nop 0
	v_addc_co_u32_e32 v7, vcc, 0, v5, vcc
	global_load_dwordx4 v[76:79], v[6:7], off offset:-4096 nt
	global_load_dwordx4 v[72:75], v[6:7], off nt
	v_add_co_u32_e32 v6, vcc, s90, v4
	v_lshl_add_u64 v[32:33], v[32:33], 0, v[2:3]
	s_nop 0
	v_addc_co_u32_e32 v7, vcc, 0, v5, vcc
	global_load_dwordx4 v[68:71], v[6:7], off offset:-4096 nt
	global_load_dwordx4 v[60:63], v[6:7], off nt
	v_add_co_u32_e32 v6, vcc, s1, v4
	s_movk_i32 s33, 0x6000
	s_nop 0
	v_addc_co_u32_e32 v7, vcc, 0, v5, vcc
	global_load_dwordx4 v[52:55], v[6:7], off offset:-4096 nt
	global_load_dwordx4 v[48:51], v[6:7], off nt
	v_add_co_u32_e32 v6, vcc, s92, v4
	v_and_b32_e32 v137, 0xffff0000, v138
	s_nop 0
	v_addc_co_u32_e32 v7, vcc, 0, v5, vcc
	global_load_dwordx4 v[40:43], v[6:7], off offset:-4096 nt
	global_load_dwordx4 v[36:39], v[6:7], off nt
	v_add_co_u32_e32 v6, vcc, s93, v4
	v_and_b32_e32 v136, 0xffff0000, v139
	s_nop 0
	v_addc_co_u32_e32 v7, vcc, 0, v5, vcc
	global_load_dwordx4 v[28:31], v[6:7], off offset:-4096 nt
	global_load_dwordx4 v[24:27], v[6:7], off nt
	v_add_co_u32_e32 v6, vcc, s6, v4
	s_nop 1
	v_addc_co_u32_e32 v7, vcc, 0, v5, vcc
	global_load_dwordx4 v[20:23], v[6:7], off offset:-4096 nt
	global_load_dwordx4 v[16:19], v[6:7], off nt
	v_add_co_u32_e32 v6, vcc, s95, v4
	s_nop 1
	v_addc_co_u32_e32 v7, vcc, 0, v5, vcc
	global_load_dwordx4 v[12:15], v[6:7], off offset:-4096 nt
	global_load_dwordx4 v[8:11], v[6:7], off nt
	v_add_co_u32_e32 v6, vcc, s52, v4
	s_nop 1
	v_addc_co_u32_e32 v7, vcc, 0, v5, vcc
	v_add_co_u32_e32 v34, vcc, s91, v32
	global_load_dwordx4 v[142:145], v[4:5], off nt
	s_nop 0
	global_load_dwordx4 v[4:7], v[6:7], off nt
	v_addc_co_u32_e32 v35, vcc, 0, v33, vcc
	global_load_dwordx4 v[124:127], v[34:35], off offset:-4096 nt
	global_load_dwordx4 v[116:119], v[34:35], off nt
	v_add_co_u32_e32 v34, vcc, s90, v32
	s_nop 1
	v_addc_co_u32_e32 v35, vcc, 0, v33, vcc
	global_load_dwordx4 v[120:123], v[34:35], off offset:-4096 nt
	global_load_dwordx4 v[108:111], v[34:35], off nt
	v_add_co_u32_e32 v34, vcc, s1, v32
	s_nop 1
	v_addc_co_u32_e32 v35, vcc, 0, v33, vcc
	global_load_dwordx4 v[112:115], v[34:35], off offset:-4096 nt
	global_load_dwordx4 v[100:103], v[34:35], off nt
	v_add_co_u32_e32 v34, vcc, s92, v32
	s_nop 1
	v_addc_co_u32_e32 v35, vcc, 0, v33, vcc
	global_load_dwordx4 v[104:107], v[34:35], off offset:-4096 nt
	global_load_dwordx4 v[92:95], v[34:35], off nt
	v_add_co_u32_e32 v34, vcc, s93, v32
	s_nop 1
	v_addc_co_u32_e32 v35, vcc, 0, v33, vcc
	global_load_dwordx4 v[96:99], v[34:35], off offset:-4096 nt
	global_load_dwordx4 v[84:87], v[34:35], off nt
	v_add_co_u32_e32 v34, vcc, s6, v32
	s_nop 1
	v_addc_co_u32_e32 v35, vcc, 0, v33, vcc
	global_load_dwordx4 v[88:91], v[34:35], off offset:-4096 nt
	global_load_dwordx4 v[64:67], v[34:35], off nt
	v_add_co_u32_e32 v34, vcc, s95, v32
	s_nop 1
	v_addc_co_u32_e32 v35, vcc, 0, v33, vcc
	global_load_dwordx4 v[56:59], v[34:35], off offset:-4096 nt
	global_load_dwordx4 v[44:47], v[34:35], off nt
	v_add_co_u32_e32 v34, vcc, s52, v32
	s_nop 1
	v_addc_co_u32_e32 v35, vcc, 0, v33, vcc
	global_load_dwordx4 v[128:131], v[32:33], off nt
	s_nop 0
	global_load_dwordx4 v[32:35], v[34:35], off nt
	v_xor_b32_e32 v138, 1, v231
	v_cmp_lt_i32_e32 vcc, v138, v235
	s_waitcnt vmcnt(17)
	v_mul_f32_e32 v139, v145, v136
	v_fmac_f32_e32 v139, v144, v82
	v_cndmask_b32_e32 v138, v231, v138, vcc
	v_lshlrev_b32_e32 v140, 2, v138
	v_mul_f32_e32 v138, v143, v137
	v_fmac_f32_e32 v138, v142, v83
	v_add_f32_e32 v138, v138, v139
	v_mul_f32_e32 v77, v77, v137
	v_fmac_f32_e32 v77, v76, v83
	v_mul_f32_e32 v76, v79, v136
	v_fmac_f32_e32 v76, v78, v82
	v_add_f32_e32 v76, v77, v76
	v_mul_f32_e32 v73, v73, v137
	v_fmac_f32_e32 v73, v72, v83
	v_mul_f32_e32 v72, v75, v136
	v_fmac_f32_e32 v72, v74, v82
	v_add_f32_e32 v72, v73, v72
	v_mul_f32_e32 v69, v69, v137
	v_fmac_f32_e32 v69, v68, v83
	v_mul_f32_e32 v68, v71, v136
	v_fmac_f32_e32 v68, v70, v82
	v_add_f32_e32 v68, v69, v68
	v_mul_f32_e32 v61, v61, v137
	v_fmac_f32_e32 v61, v60, v83
	v_mul_f32_e32 v60, v63, v136
	v_fmac_f32_e32 v60, v62, v82
	v_add_f32_e32 v60, v61, v60
	v_mul_f32_e32 v53, v53, v137
	v_fmac_f32_e32 v53, v52, v83
	v_mul_f32_e32 v52, v55, v136
	v_fmac_f32_e32 v52, v54, v82
	v_add_f32_e32 v52, v53, v52
	v_mul_f32_e32 v49, v49, v137
	v_fmac_f32_e32 v49, v48, v83
	v_mul_f32_e32 v48, v51, v136
	v_fmac_f32_e32 v48, v50, v82
	v_add_f32_e32 v48, v49, v48
	v_mul_f32_e32 v41, v41, v137
	v_fmac_f32_e32 v41, v40, v83
	v_mul_f32_e32 v40, v43, v136
	v_fmac_f32_e32 v40, v42, v82
	v_add_f32_e32 v40, v41, v40
	v_mul_f32_e32 v37, v37, v137
	v_fmac_f32_e32 v37, v36, v83
	v_mul_f32_e32 v36, v39, v136
	v_fmac_f32_e32 v36, v38, v82
	v_add_f32_e32 v36, v37, v36
	v_mul_f32_e32 v29, v29, v137
	v_fmac_f32_e32 v29, v28, v83
	v_mul_f32_e32 v28, v31, v136
	v_fmac_f32_e32 v28, v30, v82
	v_add_f32_e32 v28, v29, v28
	v_mul_f32_e32 v25, v25, v137
	v_fmac_f32_e32 v25, v24, v83
	v_mul_f32_e32 v24, v27, v136
	v_fmac_f32_e32 v24, v26, v82
	v_add_f32_e32 v24, v25, v24
	v_mul_f32_e32 v21, v21, v137
	v_fmac_f32_e32 v21, v20, v83
	v_mul_f32_e32 v20, v23, v136
	v_fmac_f32_e32 v20, v22, v82
	v_add_f32_e32 v20, v21, v20
	v_mul_f32_e32 v17, v17, v137
	v_fmac_f32_e32 v17, v16, v83
	v_mul_f32_e32 v16, v19, v136
	v_fmac_f32_e32 v16, v18, v82
	v_add_f32_e32 v16, v17, v16
	v_mul_f32_e32 v13, v13, v137
	v_fmac_f32_e32 v13, v12, v83
	v_mul_f32_e32 v12, v15, v136
	v_fmac_f32_e32 v12, v14, v82
	v_add_f32_e32 v12, v13, v12
	v_mul_f32_e32 v9, v9, v137
	v_fmac_f32_e32 v9, v8, v83
	v_mul_f32_e32 v8, v11, v136
	v_fmac_f32_e32 v8, v10, v82
	v_add_f32_e32 v8, v9, v8
	s_waitcnt vmcnt(16)
	v_mul_f32_e32 v5, v5, v137
	v_fmac_f32_e32 v5, v4, v83
	v_mul_f32_e32 v4, v7, v136
	v_fmac_f32_e32 v4, v6, v82
	v_add_f32_e32 v4, v5, v4
	v_xor_b32_e32 v141, 2, v231
	v_cmp_lt_i32_e32 vcc, v141, v235
	s_nop 1
	v_xor_b32_e32 v142, 4, v231
	v_xor_b32_e32 v143, 8, v231
	v_cndmask_b32_e32 v141, v231, v141, vcc
	v_lshlrev_b32_e32 v141, 2, v141
	v_cmp_lt_i32_e32 vcc, v142, v235
	s_nop 1
	v_readlane_b32 s1, v254, 32
	v_cmp_eq_u32_e64 s[38:39], 0, v133
	s_nop 1
	v_cndmask_b32_e32 v142, v231, v142, vcc
	v_lshlrev_b32_e32 v142, 2, v142
	v_cmp_lt_i32_e32 vcc, v143, v235
	s_nop 1
	v_cndmask_b32_e32 v143, v231, v143, vcc
	v_lshlrev_b32_e32 v143, 2, v143
	v_cmp_lt_i32_e32 vcc, v234, v235
	s_nop 1
	v_cndmask_b32_e32 v144, v231, v234, vcc
	v_lshlrev_b32_e32 v144, 2, v144
	ds_bpermute_b32 v139, v140, v138
	ds_bpermute_b32 v77, v140, v76
	ds_bpermute_b32 v73, v140, v72
	ds_bpermute_b32 v69, v140, v68
	ds_bpermute_b32 v61, v140, v60
	ds_bpermute_b32 v53, v140, v52
	ds_bpermute_b32 v49, v140, v48
	ds_bpermute_b32 v41, v140, v40
	ds_bpermute_b32 v37, v140, v36
	ds_bpermute_b32 v29, v140, v28
	ds_bpermute_b32 v25, v140, v24
	ds_bpermute_b32 v21, v140, v20
	ds_bpermute_b32 v17, v140, v16
	ds_bpermute_b32 v13, v140, v12
	ds_bpermute_b32 v9, v140, v8
	ds_bpermute_b32 v5, v140, v4
	s_waitcnt lgkmcnt(0)
	v_add_f32_e32 v138, v138, v139
	v_add_f32_e32 v76, v76, v77
	v_add_f32_e32 v72, v72, v73
	v_add_f32_e32 v68, v68, v69
	v_add_f32_e32 v60, v60, v61
	v_add_f32_e32 v52, v52, v53
	v_add_f32_e32 v48, v48, v49
	v_add_f32_e32 v40, v40, v41
	v_add_f32_e32 v36, v36, v37
	v_add_f32_e32 v28, v28, v29
	v_add_f32_e32 v24, v24, v25
	v_add_f32_e32 v20, v20, v21
	v_add_f32_e32 v16, v16, v17
	v_add_f32_e32 v12, v12, v13
	v_add_f32_e32 v8, v8, v9
	v_add_f32_e32 v4, v4, v5
	ds_bpermute_b32 v139, v141, v138
	ds_bpermute_b32 v77, v141, v76
	ds_bpermute_b32 v73, v141, v72
	ds_bpermute_b32 v69, v141, v68
	ds_bpermute_b32 v61, v141, v60
	ds_bpermute_b32 v53, v141, v52
	ds_bpermute_b32 v49, v141, v48
	ds_bpermute_b32 v41, v141, v40
	ds_bpermute_b32 v37, v141, v36
	ds_bpermute_b32 v29, v141, v28
	ds_bpermute_b32 v25, v141, v24
	ds_bpermute_b32 v21, v141, v20
	ds_bpermute_b32 v17, v141, v16
	ds_bpermute_b32 v13, v141, v12
	ds_bpermute_b32 v9, v141, v8
	ds_bpermute_b32 v5, v141, v4
	s_waitcnt lgkmcnt(0)
	v_add_f32_e32 v138, v138, v139
	v_add_f32_e32 v76, v76, v77
	v_add_f32_e32 v72, v72, v73
	v_add_f32_e32 v68, v68, v69
	v_add_f32_e32 v60, v60, v61
	v_add_f32_e32 v52, v52, v53
	v_add_f32_e32 v48, v48, v49
	v_add_f32_e32 v40, v40, v41
	v_add_f32_e32 v36, v36, v37
	v_add_f32_e32 v28, v28, v29
	v_add_f32_e32 v24, v24, v25
	v_add_f32_e32 v20, v20, v21
	v_add_f32_e32 v16, v16, v17
	v_add_f32_e32 v12, v12, v13
	v_add_f32_e32 v8, v8, v9
	v_add_f32_e32 v4, v4, v5
	ds_bpermute_b32 v139, v142, v138
	ds_bpermute_b32 v77, v142, v76
	ds_bpermute_b32 v73, v142, v72
	ds_bpermute_b32 v69, v142, v68
	ds_bpermute_b32 v61, v142, v60
	ds_bpermute_b32 v53, v142, v52
	ds_bpermute_b32 v49, v142, v48
	ds_bpermute_b32 v41, v142, v40
	ds_bpermute_b32 v37, v142, v36
	ds_bpermute_b32 v29, v142, v28
	ds_bpermute_b32 v25, v142, v24
	ds_bpermute_b32 v21, v142, v20
	ds_bpermute_b32 v17, v142, v16
	ds_bpermute_b32 v13, v142, v12
	ds_bpermute_b32 v9, v142, v8
	ds_bpermute_b32 v5, v142, v4
	s_waitcnt lgkmcnt(0)
	v_add_f32_e32 v138, v138, v139
	v_add_f32_e32 v76, v76, v77
	v_add_f32_e32 v72, v72, v73
	v_add_f32_e32 v68, v68, v69
	v_add_f32_e32 v60, v60, v61
	v_add_f32_e32 v52, v52, v53
	v_add_f32_e32 v48, v48, v49
	v_add_f32_e32 v40, v40, v41
	v_add_f32_e32 v36, v36, v37
	v_add_f32_e32 v28, v28, v29
	v_add_f32_e32 v24, v24, v25
	v_add_f32_e32 v20, v20, v21
	v_add_f32_e32 v16, v16, v17
	v_add_f32_e32 v12, v12, v13
	v_add_f32_e32 v8, v8, v9
	v_add_f32_e32 v4, v4, v5
	ds_bpermute_b32 v139, v143, v138
	ds_bpermute_b32 v77, v143, v76
	ds_bpermute_b32 v73, v143, v72
	ds_bpermute_b32 v69, v143, v68
	ds_bpermute_b32 v61, v143, v60
	ds_bpermute_b32 v53, v143, v52
	ds_bpermute_b32 v49, v143, v48
	ds_bpermute_b32 v41, v143, v40
	ds_bpermute_b32 v37, v143, v36
	ds_bpermute_b32 v29, v143, v28
	ds_bpermute_b32 v25, v143, v24
	ds_bpermute_b32 v21, v143, v20
	ds_bpermute_b32 v17, v143, v16
	ds_bpermute_b32 v13, v143, v12
	ds_bpermute_b32 v9, v143, v8
	ds_bpermute_b32 v5, v143, v4
	s_waitcnt lgkmcnt(0)
	v_add_f32_e32 v138, v138, v139
	v_add_f32_e32 v76, v76, v77
	v_add_f32_e32 v72, v72, v73
	v_add_f32_e32 v68, v68, v69
	v_add_f32_e32 v60, v60, v61
	v_add_f32_e32 v52, v52, v53
	v_add_f32_e32 v48, v48, v49
	v_add_f32_e32 v40, v40, v41
	v_add_f32_e32 v36, v36, v37
	v_add_f32_e32 v28, v28, v29
	v_add_f32_e32 v24, v24, v25
	v_add_f32_e32 v20, v20, v21
	v_add_f32_e32 v16, v16, v17
	v_add_f32_e32 v12, v12, v13
	v_add_f32_e32 v8, v8, v9
	v_add_f32_e32 v4, v4, v5
	ds_bpermute_b32 v145, v144, v138
	ds_bpermute_b32 v77, v144, v76
	ds_bpermute_b32 v73, v144, v72
	ds_bpermute_b32 v69, v144, v68
	ds_bpermute_b32 v61, v144, v60
	ds_bpermute_b32 v53, v144, v52
	ds_bpermute_b32 v49, v144, v48
	ds_bpermute_b32 v41, v144, v40
	ds_bpermute_b32 v37, v144, v36
	ds_bpermute_b32 v29, v144, v28
	ds_bpermute_b32 v25, v144, v24
	ds_bpermute_b32 v21, v144, v20
	ds_bpermute_b32 v17, v144, v16
	ds_bpermute_b32 v13, v144, v12
	ds_bpermute_b32 v9, v144, v8
	ds_bpermute_b32 v5, v144, v4
	s_waitcnt lgkmcnt(0)
	v_add_f32_e32 v138, v138, v145
	v_add_f32_e32 v76, v76, v77
	v_add_f32_e32 v72, v72, v73
	v_add_f32_e32 v68, v68, v69
	v_add_f32_e32 v60, v60, v61
	v_add_f32_e32 v52, v52, v53
	v_add_f32_e32 v48, v48, v49
	v_add_f32_e32 v40, v40, v41
	v_add_f32_e32 v36, v36, v37
	v_add_f32_e32 v28, v28, v29
	v_add_f32_e32 v24, v24, v25
	v_add_f32_e32 v20, v20, v21
	v_add_f32_e32 v16, v16, v17
	v_add_f32_e32 v12, v12, v13
	v_add_f32_e32 v8, v8, v9
	v_add_f32_e32 v4, v4, v5
	v_lshl_add_u32 v139, v146, 2, s1
	s_and_saveexec_b64 s[44:45], s[38:39]
	s_cbranch_execz .Lmy_sc_aa
	ds_write_b32 v139, v138
	ds_write_b32 v139, v76 offset:8
	ds_write_b32 v139, v72 offset:16
	ds_write_b32 v139, v68 offset:24
	ds_write_b32 v139, v60 offset:32
	ds_write_b32 v139, v52 offset:40
	ds_write_b32 v139, v48 offset:48
	ds_write_b32 v139, v40 offset:56
	ds_write_b32 v139, v36 offset:64
	ds_write_b32 v139, v28 offset:72
	ds_write_b32 v139, v24 offset:80
	ds_write_b32 v139, v20 offset:88
	ds_write_b32 v139, v16 offset:96
	ds_write_b32 v139, v12 offset:104
	ds_write_b32 v139, v8 offset:112
	ds_write_b32 v139, v4 offset:120

.LBB0_592:
	s_or_b64 exec, exec, s[44:45]
	v_and_b32_e32 v147, 0xffff0000, v134
	v_lshlrev_b32_e32 v137, 16, v134
	v_and_b32_e32 v134, 0xffff0000, v135
	s_waitcnt vmcnt(31)
	v_mul_f32_e32 v81, v81, v147
	v_lshlrev_b32_e32 v136, 16, v135
	v_fmac_f32_e32 v81, v80, v137
	v_mul_f32_e32 v80, v83, v134
	v_fmac_f32_e32 v80, v82, v136
	v_add_f32_e32 v80, v81, v80
	s_waitcnt vmcnt(30)
	v_mul_f32_e32 v77, v77, v147
	v_fmac_f32_e32 v77, v76, v137
	v_mul_f32_e32 v76, v79, v134
	v_fmac_f32_e32 v76, v78, v136
	v_add_f32_e32 v76, v77, v76
	s_waitcnt vmcnt(29)
	v_mul_f32_e32 v73, v73, v147
	v_fmac_f32_e32 v73, v72, v137
	v_mul_f32_e32 v72, v75, v134
	v_fmac_f32_e32 v72, v74, v136
	v_add_f32_e32 v72, v73, v72
	s_waitcnt vmcnt(28)
	v_mul_f32_e32 v69, v69, v147
	v_fmac_f32_e32 v69, v68, v137
	v_mul_f32_e32 v68, v71, v134
	v_fmac_f32_e32 v68, v70, v136
	v_add_f32_e32 v68, v69, v68
	s_waitcnt vmcnt(27)
	v_mul_f32_e32 v61, v61, v147
	v_fmac_f32_e32 v61, v60, v137
	v_mul_f32_e32 v60, v63, v134
	v_fmac_f32_e32 v60, v62, v136
	v_add_f32_e32 v60, v61, v60
	s_waitcnt vmcnt(26)
	v_mul_f32_e32 v53, v53, v147
	v_fmac_f32_e32 v53, v52, v137
	v_mul_f32_e32 v52, v55, v134
	v_fmac_f32_e32 v52, v54, v136
	v_add_f32_e32 v52, v53, v52
	s_waitcnt vmcnt(25)
	v_mul_f32_e32 v49, v49, v147
	v_fmac_f32_e32 v49, v48, v137
	v_mul_f32_e32 v48, v51, v134
	v_fmac_f32_e32 v48, v50, v136
	v_add_f32_e32 v48, v49, v48
	s_waitcnt vmcnt(24)
	v_mul_f32_e32 v41, v41, v147
	v_fmac_f32_e32 v41, v40, v137
	v_mul_f32_e32 v40, v43, v134
	v_fmac_f32_e32 v40, v42, v136
	v_add_f32_e32 v40, v41, v40
	s_waitcnt vmcnt(23)
	v_mul_f32_e32 v37, v37, v147
	v_fmac_f32_e32 v37, v36, v137
	v_mul_f32_e32 v36, v39, v134
	v_fmac_f32_e32 v36, v38, v136
	v_add_f32_e32 v36, v37, v36
	s_waitcnt vmcnt(22)
	v_mul_f32_e32 v29, v29, v147
	v_fmac_f32_e32 v29, v28, v137
	v_mul_f32_e32 v28, v31, v134
	v_fmac_f32_e32 v28, v30, v136
	v_add_f32_e32 v28, v29, v28
	s_waitcnt vmcnt(21)
	v_mul_f32_e32 v25, v25, v147
	v_fmac_f32_e32 v25, v24, v137
	v_mul_f32_e32 v24, v27, v134
	v_fmac_f32_e32 v24, v26, v136
	v_add_f32_e32 v24, v25, v24
	s_waitcnt vmcnt(20)
	v_mul_f32_e32 v21, v21, v147
	v_fmac_f32_e32 v21, v20, v137
	v_mul_f32_e32 v20, v23, v134
	v_fmac_f32_e32 v20, v22, v136
	v_add_f32_e32 v20, v21, v20
	s_waitcnt vmcnt(19)
	v_mul_f32_e32 v17, v17, v147
	v_fmac_f32_e32 v17, v16, v137
	v_mul_f32_e32 v16, v19, v134
	v_fmac_f32_e32 v16, v18, v136
	v_add_f32_e32 v16, v17, v16
	s_waitcnt vmcnt(18)
	v_mul_f32_e32 v13, v13, v147
	v_fmac_f32_e32 v13, v12, v137
	v_mul_f32_e32 v12, v15, v134
	v_fmac_f32_e32 v12, v14, v136
	v_add_f32_e32 v12, v13, v12
	s_waitcnt vmcnt(17)
	v_mul_f32_e32 v9, v9, v147
	v_fmac_f32_e32 v9, v8, v137
	v_mul_f32_e32 v8, v11, v134
	v_fmac_f32_e32 v8, v10, v136
	v_add_f32_e32 v8, v9, v8
	s_waitcnt vmcnt(16)
	v_mul_f32_e32 v5, v5, v147
	v_fmac_f32_e32 v5, v4, v137
	v_mul_f32_e32 v4, v7, v134
	v_fmac_f32_e32 v4, v6, v136
	v_add_f32_e32 v4, v5, v4
	ds_bpermute_b32 v81, v140, v80
	ds_bpermute_b32 v77, v140, v76
	ds_bpermute_b32 v73, v140, v72
	ds_bpermute_b32 v69, v140, v68
	ds_bpermute_b32 v61, v140, v60
	ds_bpermute_b32 v53, v140, v52
	ds_bpermute_b32 v49, v140, v48
	ds_bpermute_b32 v41, v140, v40
	ds_bpermute_b32 v37, v140, v36
	ds_bpermute_b32 v29, v140, v28
	ds_bpermute_b32 v25, v140, v24
	ds_bpermute_b32 v21, v140, v20
	ds_bpermute_b32 v17, v140, v16
	ds_bpermute_b32 v13, v140, v12
	ds_bpermute_b32 v9, v140, v8
	ds_bpermute_b32 v5, v140, v4
	s_waitcnt lgkmcnt(0)
	v_add_f32_e32 v80, v80, v81
	v_add_f32_e32 v76, v76, v77
	v_add_f32_e32 v72, v72, v73
	v_add_f32_e32 v68, v68, v69
	v_add_f32_e32 v60, v60, v61
	v_add_f32_e32 v52, v52, v53
	v_add_f32_e32 v48, v48, v49
	v_add_f32_e32 v40, v40, v41
	v_add_f32_e32 v36, v36, v37
	v_add_f32_e32 v28, v28, v29
	v_add_f32_e32 v24, v24, v25
	v_add_f32_e32 v20, v20, v21
	v_add_f32_e32 v16, v16, v17
	v_add_f32_e32 v12, v12, v13
	v_add_f32_e32 v8, v8, v9
	v_add_f32_e32 v4, v4, v5
	ds_bpermute_b32 v81, v141, v80
	ds_bpermute_b32 v77, v141, v76
	ds_bpermute_b32 v73, v141, v72
	ds_bpermute_b32 v69, v141, v68
	ds_bpermute_b32 v61, v141, v60
	ds_bpermute_b32 v53, v141, v52
	ds_bpermute_b32 v49, v141, v48
	ds_bpermute_b32 v41, v141, v40
	ds_bpermute_b32 v37, v141, v36
	ds_bpermute_b32 v29, v141, v28
	ds_bpermute_b32 v25, v141, v24
	ds_bpermute_b32 v21, v141, v20
	ds_bpermute_b32 v17, v141, v16
	ds_bpermute_b32 v13, v141, v12
	ds_bpermute_b32 v9, v141, v8
	ds_bpermute_b32 v5, v141, v4
	s_waitcnt lgkmcnt(0)
	v_add_f32_e32 v80, v80, v81
	v_add_f32_e32 v76, v76, v77
	v_add_f32_e32 v72, v72, v73
	v_add_f32_e32 v68, v68, v69
	v_add_f32_e32 v60, v60, v61
	v_add_f32_e32 v52, v52, v53
	v_add_f32_e32 v48, v48, v49
	v_add_f32_e32 v40, v40, v41
	v_add_f32_e32 v36, v36, v37
	v_add_f32_e32 v28, v28, v29
	v_add_f32_e32 v24, v24, v25
	v_add_f32_e32 v20, v20, v21
	v_add_f32_e32 v16, v16, v17
	v_add_f32_e32 v12, v12, v13
	v_add_f32_e32 v8, v8, v9
	v_add_f32_e32 v4, v4, v5
	ds_bpermute_b32 v81, v142, v80
	ds_bpermute_b32 v77, v142, v76
	ds_bpermute_b32 v73, v142, v72
	ds_bpermute_b32 v69, v142, v68
	ds_bpermute_b32 v61, v142, v60
	ds_bpermute_b32 v53, v142, v52
	ds_bpermute_b32 v49, v142, v48
	ds_bpermute_b32 v41, v142, v40
	ds_bpermute_b32 v37, v142, v36
	ds_bpermute_b32 v29, v142, v28
	ds_bpermute_b32 v25, v142, v24
	ds_bpermute_b32 v21, v142, v20
	ds_bpermute_b32 v17, v142, v16
	ds_bpermute_b32 v13, v142, v12
	ds_bpermute_b32 v9, v142, v8
	ds_bpermute_b32 v5, v142, v4
	s_waitcnt lgkmcnt(0)
	v_add_f32_e32 v80, v80, v81
	v_add_f32_e32 v76, v76, v77
	v_add_f32_e32 v72, v72, v73
	v_add_f32_e32 v68, v68, v69
	v_add_f32_e32 v60, v60, v61
	v_add_f32_e32 v52, v52, v53
	v_add_f32_e32 v48, v48, v49
	v_add_f32_e32 v40, v40, v41
	v_add_f32_e32 v36, v36, v37
	v_add_f32_e32 v28, v28, v29
	v_add_f32_e32 v24, v24, v25
	v_add_f32_e32 v20, v20, v21
	v_add_f32_e32 v16, v16, v17
	v_add_f32_e32 v12, v12, v13
	v_add_f32_e32 v8, v8, v9
	v_add_f32_e32 v4, v4, v5
	ds_bpermute_b32 v81, v143, v80
	ds_bpermute_b32 v77, v143, v76
	ds_bpermute_b32 v73, v143, v72
	ds_bpermute_b32 v69, v143, v68
	ds_bpermute_b32 v61, v143, v60
	ds_bpermute_b32 v53, v143, v52
	ds_bpermute_b32 v49, v143, v48
	ds_bpermute_b32 v41, v143, v40
	ds_bpermute_b32 v37, v143, v36
	ds_bpermute_b32 v29, v143, v28
	ds_bpermute_b32 v25, v143, v24
	ds_bpermute_b32 v21, v143, v20
	ds_bpermute_b32 v17, v143, v16
	ds_bpermute_b32 v13, v143, v12
	ds_bpermute_b32 v9, v143, v8
	ds_bpermute_b32 v5, v143, v4
	s_waitcnt lgkmcnt(0)
	v_add_f32_e32 v80, v80, v81
	v_add_f32_e32 v76, v76, v77
	v_add_f32_e32 v72, v72, v73
	v_add_f32_e32 v68, v68, v69
	v_add_f32_e32 v60, v60, v61
	v_add_f32_e32 v52, v52, v53
	v_add_f32_e32 v48, v48, v49
	v_add_f32_e32 v40, v40, v41
	v_add_f32_e32 v36, v36, v37
	v_add_f32_e32 v28, v28, v29
	v_add_f32_e32 v24, v24, v25
	v_add_f32_e32 v20, v20, v21
	v_add_f32_e32 v16, v16, v17
	v_add_f32_e32 v12, v12, v13
	v_add_f32_e32 v8, v8, v9
	v_add_f32_e32 v4, v4, v5
	ds_bpermute_b32 v81, v144, v80
	ds_bpermute_b32 v77, v144, v76
	ds_bpermute_b32 v73, v144, v72
	ds_bpermute_b32 v69, v144, v68
	ds_bpermute_b32 v61, v144, v60
	ds_bpermute_b32 v53, v144, v52
	ds_bpermute_b32 v49, v144, v48
	ds_bpermute_b32 v41, v144, v40
	ds_bpermute_b32 v37, v144, v36
	ds_bpermute_b32 v29, v144, v28
	ds_bpermute_b32 v25, v144, v24
	ds_bpermute_b32 v21, v144, v20
	ds_bpermute_b32 v17, v144, v16
	ds_bpermute_b32 v13, v144, v12
	ds_bpermute_b32 v9, v144, v8
	ds_bpermute_b32 v5, v144, v4
	s_waitcnt lgkmcnt(0)
	v_add_f32_e32 v80, v80, v81
	v_add_f32_e32 v76, v76, v77
	v_add_f32_e32 v72, v72, v73
	v_add_f32_e32 v68, v68, v69
	v_add_f32_e32 v60, v60, v61
	v_add_f32_e32 v52, v52, v53
	v_add_f32_e32 v48, v48, v49
	v_add_f32_e32 v40, v40, v41
	v_add_f32_e32 v36, v36, v37
	v_add_f32_e32 v28, v28, v29
	v_add_f32_e32 v24, v24, v25
	v_add_f32_e32 v20, v20, v21
	v_add_f32_e32 v16, v16, v17
	v_add_f32_e32 v12, v12, v13
	v_add_f32_e32 v8, v8, v9
	v_add_f32_e32 v4, v4, v5
	s_and_saveexec_b64 s[44:45], s[38:39]
	s_cbranch_execz .Lmy_sc_ab
	ds_write_b32 v139, v80 offset:1024
	ds_write_b32 v139, v76 offset:1032
	ds_write_b32 v139, v72 offset:1040
	ds_write_b32 v139, v68 offset:1048
	ds_write_b32 v139, v60 offset:1056
	ds_write_b32 v139, v52 offset:1064
	ds_write_b32 v139, v48 offset:1072
	ds_write_b32 v139, v40 offset:1080
	ds_write_b32 v139, v36 offset:1088
	ds_write_b32 v139, v28 offset:1096
	ds_write_b32 v139, v24 offset:1104
	ds_write_b32 v139, v20 offset:1112
	ds_write_b32 v139, v16 offset:1120
	ds_write_b32 v139, v12 offset:1128
	ds_write_b32 v139, v8 offset:1136
	ds_write_b32 v139, v4 offset:1144

.LBB0_682:
	s_cmp_eq_u32 s14, s58
	s_mov_b64 s[40:41], -1
	s_cbranch_scc1 .LBB0_756
	v_mov_b32_e32 v132, v204
	v_readlane_b32 s2, v253, 11
	v_and_b32_e32 v133, 31, v132
	v_lshlrev_b32_e32 v2, 3, v133
	global_load_dwordx2 v[142:143], v2, s[50:51]
	global_load_dwordx2 v[134:135], v2, s[66:67]
	v_readlane_b32 s3, v253, 12
	v_bfe_u32 v144, v132, 5, 1
	s_load_dwordx4 s[44:47], s[2:3], 0x10
	v_or_b32_e32 v4, s89, v144
	v_ashrrev_i32_e32 v5, 31, v4
	v_lshlrev_b64 v[80:81], 9, v[4:5]
	v_lshl_add_u64 v[4:5], s[48:49], 0, v[80:81]
	v_lshlrev_b64 v[4:5], 2, v[4:5]
	v_lshlrev_b32_e32 v2, 4, v133
	s_waitcnt lgkmcnt(0)
	v_lshl_add_u64 v[6:7], s[44:45], 0, v[4:5]
	v_lshl_add_u64 v[40:41], s[46:47], 0, v[4:5]
	v_lshl_add_u64 v[4:5], v[6:7], 0, v[2:3]
	s_waitcnt vmcnt(1)
	v_lshlrev_b32_e32 v83, 16, v142
	v_lshlrev_b32_e32 v82, 16, v143
	s_movk_i32 s14, 0x2000
	v_add_co_u32_e32 v6, vcc, s14, v4
	s_movk_i32 s24, 0x4000
	s_nop 0
	v_addc_co_u32_e32 v7, vcc, 0, v5, vcc
	global_load_dwordx4 v[76:79], v[6:7], off offset:-4096 nt
	global_load_dwordx4 v[68:71], v[6:7], off nt
	v_add_co_u32_e32 v6, vcc, s24, v4
	s_movk_i32 s40, 0x6000
	s_nop 0
	v_addc_co_u32_e32 v7, vcc, 0, v5, vcc
	global_load_dwordx4 v[60:63], v[6:7], off offset:-4096 nt
	global_load_dwordx4 v[56:59], v[6:7], off nt
	v_add_co_u32_e32 v6, vcc, s40, v4
	s_mov_b32 s41, 0x8000
	s_nop 0
	v_addc_co_u32_e32 v7, vcc, 0, v5, vcc
	global_load_dwordx4 v[48:51], v[6:7], off offset:-4096 nt
	global_load_dwordx4 v[44:47], v[6:7], off nt
	v_add_co_u32_e32 v6, vcc, s41, v4
	s_mov_b32 s42, 0xa000
	s_nop 0
	v_addc_co_u32_e32 v7, vcc, 0, v5, vcc
	global_load_dwordx4 v[36:39], v[6:7], off offset:-4096 nt
	global_load_dwordx4 v[32:35], v[6:7], off nt
	v_add_co_u32_e32 v6, vcc, s42, v4
	s_mov_b32 s31, 0xe000
	s_nop 0
	v_addc_co_u32_e32 v7, vcc, 0, v5, vcc
	global_load_dwordx4 v[28:31], v[6:7], off offset:-4096 nt
	global_load_dwordx4 v[24:27], v[6:7], off nt
	v_add_co_u32_e32 v6, vcc, s6, v4
	s_mov_b32 s43, 0xf000
	s_nop 0
	v_addc_co_u32_e32 v7, vcc, 0, v5, vcc
	global_load_dwordx4 v[20:23], v[6:7], off offset:-4096 nt
	global_load_dwordx4 v[16:19], v[6:7], off nt
	v_add_co_u32_e32 v6, vcc, s31, v4
	v_lshl_add_u64 v[40:41], v[40:41], 0, v[2:3]
	s_nop 0
	v_addc_co_u32_e32 v7, vcc, 0, v5, vcc
	global_load_dwordx4 v[12:15], v[6:7], off offset:-4096 nt
	global_load_dwordx4 v[8:11], v[6:7], off nt
	v_add_co_u32_e32 v6, vcc, s43, v4
	s_movk_i32 s63, 0x2000
	s_nop 0
	v_addc_co_u32_e32 v7, vcc, 0, v5, vcc
	v_add_co_u32_e32 v42, vcc, s14, v40
	global_load_dwordx4 v[138:141], v[4:5], off nt
	s_nop 0
	global_load_dwordx4 v[4:7], v[6:7], off nt
	v_addc_co_u32_e32 v43, vcc, 0, v41, vcc
	global_load_dwordx4 v[124:127], v[42:43], off offset:-4096 nt
	global_load_dwordx4 v[116:119], v[42:43], off nt
	v_add_co_u32_e32 v42, vcc, s24, v40
	s_movk_i32 s14, 0x4000
	s_nop 0
	v_addc_co_u32_e32 v43, vcc, 0, v41, vcc
	global_load_dwordx4 v[120:123], v[42:43], off offset:-4096 nt
	global_load_dwordx4 v[108:111], v[42:43], off nt
	v_add_co_u32_e32 v42, vcc, s40, v40
	s_movk_i32 s33, 0x6000
	s_nop 0
	v_addc_co_u32_e32 v43, vcc, 0, v41, vcc
	global_load_dwordx4 v[112:115], v[42:43], off offset:-4096 nt
	global_load_dwordx4 v[100:103], v[42:43], off nt
	v_add_co_u32_e32 v42, vcc, s41, v40
	s_mov_b32 s24, 0x8000
	s_nop 0
	v_addc_co_u32_e32 v43, vcc, 0, v41, vcc
	global_load_dwordx4 v[104:107], v[42:43], off offset:-4096 nt
	global_load_dwordx4 v[92:95], v[42:43], off nt
	v_add_co_u32_e32 v42, vcc, s42, v40
	s_mov_b32 s20, 0xa000
	s_nop 0
	v_addc_co_u32_e32 v43, vcc, 0, v41, vcc
	global_load_dwordx4 v[96:99], v[42:43], off offset:-4096 nt
	global_load_dwordx4 v[84:87], v[42:43], off nt
	v_add_co_u32_e32 v42, vcc, s6, v40
	s_mov_b32 s30, 0xe000
	s_nop 0
	v_addc_co_u32_e32 v43, vcc, 0, v41, vcc
	global_load_dwordx4 v[88:91], v[42:43], off offset:-4096 nt
	global_load_dwordx4 v[72:75], v[42:43], off nt
	v_add_co_u32_e32 v42, vcc, s31, v40
	v_and_b32_e32 v137, 0xffff0000, v142
	s_nop 0
	v_addc_co_u32_e32 v43, vcc, 0, v41, vcc
	global_load_dwordx4 v[64:67], v[42:43], off offset:-4096 nt
	global_load_dwordx4 v[52:55], v[42:43], off nt
	v_add_co_u32_e32 v42, vcc, s43, v40
	v_and_b32_e32 v136, 0xffff0000, v143
	s_nop 0
	v_addc_co_u32_e32 v43, vcc, 0, v41, vcc
	global_load_dwordx4 v[128:131], v[40:41], off nt
	s_nop 0
	global_load_dwordx4 v[40:43], v[42:43], off nt
	s_waitcnt vmcnt(17)
	v_mul_f32_e32 v139, v139, v137
	v_fmac_f32_e32 v139, v138, v83
	v_mul_f32_e32 v138, v141, v136
	v_fmac_f32_e32 v138, v140, v82
	v_add_f32_e32 v138, v139, v138
	v_mul_f32_e32 v77, v77, v137
	v_fmac_f32_e32 v77, v76, v83
	v_mul_f32_e32 v76, v79, v136
	v_fmac_f32_e32 v76, v78, v82
	v_add_f32_e32 v76, v77, v76
	v_mul_f32_e32 v69, v69, v137
	v_fmac_f32_e32 v69, v68, v83
	v_mul_f32_e32 v68, v71, v136
	v_fmac_f32_e32 v68, v70, v82
	v_add_f32_e32 v68, v69, v68
	v_mul_f32_e32 v61, v61, v137
	v_fmac_f32_e32 v61, v60, v83
	v_mul_f32_e32 v60, v63, v136
	v_fmac_f32_e32 v60, v62, v82
	v_add_f32_e32 v60, v61, v60
	v_mul_f32_e32 v57, v57, v137
	v_fmac_f32_e32 v57, v56, v83
	v_mul_f32_e32 v56, v59, v136
	v_fmac_f32_e32 v56, v58, v82
	v_add_f32_e32 v56, v57, v56
	v_mul_f32_e32 v49, v49, v137
	v_fmac_f32_e32 v49, v48, v83
	v_mul_f32_e32 v48, v51, v136
	v_fmac_f32_e32 v48, v50, v82
	v_add_f32_e32 v48, v49, v48
	v_mul_f32_e32 v45, v45, v137
	v_fmac_f32_e32 v45, v44, v83
	v_mul_f32_e32 v44, v47, v136
	v_fmac_f32_e32 v44, v46, v82
	v_add_f32_e32 v44, v45, v44
	v_mul_f32_e32 v37, v37, v137
	v_fmac_f32_e32 v37, v36, v83
	v_mul_f32_e32 v36, v39, v136
	v_fmac_f32_e32 v36, v38, v82
	v_add_f32_e32 v36, v37, v36
	v_mul_f32_e32 v33, v33, v137
	v_fmac_f32_e32 v33, v32, v83
	v_mul_f32_e32 v32, v35, v136
	v_fmac_f32_e32 v32, v34, v82
	v_add_f32_e32 v32, v33, v32
	v_mul_f32_e32 v29, v29, v137
	v_fmac_f32_e32 v29, v28, v83
	v_mul_f32_e32 v28, v31, v136
	v_fmac_f32_e32 v28, v30, v82
	v_add_f32_e32 v28, v29, v28
	v_mul_f32_e32 v25, v25, v137
	v_fmac_f32_e32 v25, v24, v83
	v_mul_f32_e32 v24, v27, v136
	v_fmac_f32_e32 v24, v26, v82
	v_add_f32_e32 v24, v25, v24
	v_mul_f32_e32 v21, v21, v137
	v_fmac_f32_e32 v21, v20, v83
	v_mul_f32_e32 v20, v23, v136
	v_fmac_f32_e32 v20, v22, v82
	v_add_f32_e32 v20, v21, v20
	v_mul_f32_e32 v17, v17, v137
	v_fmac_f32_e32 v17, v16, v83
	v_mul_f32_e32 v16, v19, v136
	v_fmac_f32_e32 v16, v18, v82
	v_add_f32_e32 v16, v17, v16
	v_mul_f32_e32 v13, v13, v137
	v_fmac_f32_e32 v13, v12, v83
	v_mul_f32_e32 v12, v15, v136
	v_fmac_f32_e32 v12, v14, v82
	v_add_f32_e32 v12, v13, v12
	v_mul_f32_e32 v9, v9, v137
	v_fmac_f32_e32 v9, v8, v83
	v_mul_f32_e32 v8, v11, v136
	v_fmac_f32_e32 v8, v10, v82
	v_add_f32_e32 v8, v9, v8
	s_waitcnt vmcnt(16)
	v_mul_f32_e32 v5, v5, v137
	v_fmac_f32_e32 v5, v4, v83
	v_mul_f32_e32 v4, v7, v136
	v_fmac_f32_e32 v4, v6, v82
	v_add_f32_e32 v4, v5, v4
	v_cmp_eq_u32_e64 s[40:41], 0, v133
	s_nop 1
	ds_bpermute_b32 v139, v205, v138
	ds_bpermute_b32 v77, v205, v76
	ds_bpermute_b32 v69, v205, v68
	ds_bpermute_b32 v61, v205, v60
	ds_bpermute_b32 v57, v205, v56
	ds_bpermute_b32 v49, v205, v48
	ds_bpermute_b32 v45, v205, v44
	ds_bpermute_b32 v37, v205, v36
	ds_bpermute_b32 v33, v205, v32
	ds_bpermute_b32 v29, v205, v28
	ds_bpermute_b32 v25, v205, v24
	ds_bpermute_b32 v21, v205, v20
	ds_bpermute_b32 v17, v205, v16
	ds_bpermute_b32 v13, v205, v12
	ds_bpermute_b32 v9, v205, v8
	ds_bpermute_b32 v5, v205, v4
	s_waitcnt lgkmcnt(0)
	v_add_f32_e32 v138, v138, v139
	v_add_f32_e32 v76, v76, v77
	v_add_f32_e32 v68, v68, v69
	v_add_f32_e32 v60, v60, v61
	v_add_f32_e32 v56, v56, v57
	v_add_f32_e32 v48, v48, v49
	v_add_f32_e32 v44, v44, v45
	v_add_f32_e32 v36, v36, v37
	v_add_f32_e32 v32, v32, v33
	v_add_f32_e32 v28, v28, v29
	v_add_f32_e32 v24, v24, v25
	v_add_f32_e32 v20, v20, v21
	v_add_f32_e32 v16, v16, v17
	v_add_f32_e32 v12, v12, v13
	v_add_f32_e32 v8, v8, v9
	v_add_f32_e32 v4, v4, v5
	ds_bpermute_b32 v139, v206, v138
	ds_bpermute_b32 v77, v206, v76
	ds_bpermute_b32 v69, v206, v68
	ds_bpermute_b32 v61, v206, v60
	ds_bpermute_b32 v57, v206, v56
	ds_bpermute_b32 v49, v206, v48
	ds_bpermute_b32 v45, v206, v44
	ds_bpermute_b32 v37, v206, v36
	ds_bpermute_b32 v33, v206, v32
	ds_bpermute_b32 v29, v206, v28
	ds_bpermute_b32 v25, v206, v24
	ds_bpermute_b32 v21, v206, v20
	ds_bpermute_b32 v17, v206, v16
	ds_bpermute_b32 v13, v206, v12
	ds_bpermute_b32 v9, v206, v8
	ds_bpermute_b32 v5, v206, v4
	s_waitcnt lgkmcnt(0)
	v_add_f32_e32 v138, v138, v139
	v_add_f32_e32 v76, v76, v77
	v_add_f32_e32 v68, v68, v69
	v_add_f32_e32 v60, v60, v61
	v_add_f32_e32 v56, v56, v57
	v_add_f32_e32 v48, v48, v49
	v_add_f32_e32 v44, v44, v45
	v_add_f32_e32 v36, v36, v37
	v_add_f32_e32 v32, v32, v33
	v_add_f32_e32 v28, v28, v29
	v_add_f32_e32 v24, v24, v25
	v_add_f32_e32 v20, v20, v21
	v_add_f32_e32 v16, v16, v17
	v_add_f32_e32 v12, v12, v13
	v_add_f32_e32 v8, v8, v9
	v_add_f32_e32 v4, v4, v5
	ds_bpermute_b32 v139, v207, v138
	ds_bpermute_b32 v77, v207, v76
	ds_bpermute_b32 v69, v207, v68
	ds_bpermute_b32 v61, v207, v60
	ds_bpermute_b32 v57, v207, v56
	ds_bpermute_b32 v49, v207, v48
	ds_bpermute_b32 v45, v207, v44
	ds_bpermute_b32 v37, v207, v36
	ds_bpermute_b32 v33, v207, v32
	ds_bpermute_b32 v29, v207, v28
	ds_bpermute_b32 v25, v207, v24
	ds_bpermute_b32 v21, v207, v20
	ds_bpermute_b32 v17, v207, v16
	ds_bpermute_b32 v13, v207, v12
	ds_bpermute_b32 v9, v207, v8
	ds_bpermute_b32 v5, v207, v4
	s_waitcnt lgkmcnt(0)
	v_add_f32_e32 v138, v138, v139
	v_add_f32_e32 v76, v76, v77
	v_add_f32_e32 v68, v68, v69
	v_add_f32_e32 v60, v60, v61
	v_add_f32_e32 v56, v56, v57
	v_add_f32_e32 v48, v48, v49
	v_add_f32_e32 v44, v44, v45
	v_add_f32_e32 v36, v36, v37
	v_add_f32_e32 v32, v32, v33
	v_add_f32_e32 v28, v28, v29
	v_add_f32_e32 v24, v24, v25
	v_add_f32_e32 v20, v20, v21
	v_add_f32_e32 v16, v16, v17
	v_add_f32_e32 v12, v12, v13
	v_add_f32_e32 v8, v8, v9
	v_add_f32_e32 v4, v4, v5
	ds_bpermute_b32 v139, v208, v138
	ds_bpermute_b32 v77, v208, v76
	ds_bpermute_b32 v69, v208, v68
	ds_bpermute_b32 v61, v208, v60
	ds_bpermute_b32 v57, v208, v56
	ds_bpermute_b32 v49, v208, v48
	ds_bpermute_b32 v45, v208, v44
	ds_bpermute_b32 v37, v208, v36
	ds_bpermute_b32 v33, v208, v32
	ds_bpermute_b32 v29, v208, v28
	ds_bpermute_b32 v25, v208, v24
	ds_bpermute_b32 v21, v208, v20
	ds_bpermute_b32 v17, v208, v16
	ds_bpermute_b32 v13, v208, v12
	ds_bpermute_b32 v9, v208, v8
	ds_bpermute_b32 v5, v208, v4
	s_waitcnt lgkmcnt(0)
	v_add_f32_e32 v139, v138, v139
	v_add_f32_e32 v76, v76, v77
	v_add_f32_e32 v68, v68, v69
	v_add_f32_e32 v60, v60, v61
	v_add_f32_e32 v56, v56, v57
	v_add_f32_e32 v48, v48, v49
	v_add_f32_e32 v44, v44, v45
	v_add_f32_e32 v36, v36, v37
	v_add_f32_e32 v32, v32, v33
	v_add_f32_e32 v28, v28, v29
	v_add_f32_e32 v24, v24, v25
	v_add_f32_e32 v20, v20, v21
	v_add_f32_e32 v16, v16, v17
	v_add_f32_e32 v12, v12, v13
	v_add_f32_e32 v8, v8, v9
	v_add_f32_e32 v4, v4, v5
	ds_bpermute_b32 v140, v209, v139
	ds_bpermute_b32 v77, v209, v76
	ds_bpermute_b32 v69, v209, v68
	ds_bpermute_b32 v61, v209, v60
	ds_bpermute_b32 v57, v209, v56
	ds_bpermute_b32 v49, v209, v48
	ds_bpermute_b32 v45, v209, v44
	ds_bpermute_b32 v37, v209, v36
	ds_bpermute_b32 v33, v209, v32
	ds_bpermute_b32 v29, v209, v28
	ds_bpermute_b32 v25, v209, v24
	ds_bpermute_b32 v21, v209, v20
	ds_bpermute_b32 v17, v209, v16
	ds_bpermute_b32 v13, v209, v12
	ds_bpermute_b32 v9, v209, v8
	ds_bpermute_b32 v5, v209, v4
	s_waitcnt lgkmcnt(0)
	v_add_f32_e32 v139, v139, v140
	v_add_f32_e32 v76, v76, v77
	v_add_f32_e32 v68, v68, v69
	v_add_f32_e32 v60, v60, v61
	v_add_f32_e32 v56, v56, v57
	v_add_f32_e32 v48, v48, v49
	v_add_f32_e32 v44, v44, v45
	v_add_f32_e32 v36, v36, v37
	v_add_f32_e32 v32, v32, v33
	v_add_f32_e32 v28, v28, v29
	v_add_f32_e32 v24, v24, v25
	v_add_f32_e32 v20, v20, v21
	v_add_f32_e32 v16, v16, v17
	v_add_f32_e32 v12, v12, v13
	v_add_f32_e32 v8, v8, v9
	v_add_f32_e32 v4, v4, v5
	v_lshl_add_u32 v138, v144, 2, s90
	s_and_saveexec_b64 s[42:43], s[40:41]
	s_cbranch_execz .Lmy_sc_la
	ds_write_b32 v138, v139
	ds_write_b32 v138, v76 offset:8
	ds_write_b32 v138, v68 offset:16
	ds_write_b32 v138, v60 offset:24
	ds_write_b32 v138, v56 offset:32
	ds_write_b32 v138, v48 offset:40
	ds_write_b32 v138, v44 offset:48
	ds_write_b32 v138, v36 offset:56
	ds_write_b32 v138, v32 offset:64
	ds_write_b32 v138, v28 offset:72
	ds_write_b32 v138, v24 offset:80
	ds_write_b32 v138, v20 offset:88
	ds_write_b32 v138, v16 offset:96
	ds_write_b32 v138, v12 offset:104
	ds_write_b32 v138, v8 offset:112
	ds_write_b32 v138, v4 offset:120

.LBB0_719:
	s_or_b64 exec, exec, s[46:47]
	v_and_b32_e32 v141, 0xffff0000, v134
	v_lshlrev_b32_e32 v137, 16, v134
	v_and_b32_e32 v134, 0xffff0000, v135
	s_waitcnt vmcnt(31)
	v_mul_f32_e32 v81, v81, v141
	v_lshlrev_b32_e32 v136, 16, v135
	v_fmac_f32_e32 v81, v80, v137
	v_mul_f32_e32 v80, v83, v134
	v_fmac_f32_e32 v80, v82, v136
	v_add_f32_e32 v80, v81, v80
	s_waitcnt vmcnt(30)
	v_mul_f32_e32 v77, v77, v141
	v_fmac_f32_e32 v77, v76, v137
	v_mul_f32_e32 v76, v79, v134
	v_fmac_f32_e32 v76, v78, v136
	v_add_f32_e32 v76, v77, v76
	s_waitcnt vmcnt(29)
	v_mul_f32_e32 v69, v69, v141
	v_fmac_f32_e32 v69, v68, v137
	v_mul_f32_e32 v68, v71, v134
	v_fmac_f32_e32 v68, v70, v136
	v_add_f32_e32 v68, v69, v68
	s_waitcnt vmcnt(28)
	v_mul_f32_e32 v61, v61, v141
	v_fmac_f32_e32 v61, v60, v137
	v_mul_f32_e32 v60, v63, v134
	v_fmac_f32_e32 v60, v62, v136
	v_add_f32_e32 v60, v61, v60
	s_waitcnt vmcnt(27)
	v_mul_f32_e32 v57, v57, v141
	v_fmac_f32_e32 v57, v56, v137
	v_mul_f32_e32 v56, v59, v134
	v_fmac_f32_e32 v56, v58, v136
	v_add_f32_e32 v56, v57, v56
	s_waitcnt vmcnt(26)
	v_mul_f32_e32 v49, v49, v141
	v_fmac_f32_e32 v49, v48, v137
	v_mul_f32_e32 v48, v51, v134
	v_fmac_f32_e32 v48, v50, v136
	v_add_f32_e32 v48, v49, v48
	s_waitcnt vmcnt(25)
	v_mul_f32_e32 v45, v45, v141
	v_fmac_f32_e32 v45, v44, v137
	v_mul_f32_e32 v44, v47, v134
	v_fmac_f32_e32 v44, v46, v136
	v_add_f32_e32 v44, v45, v44
	s_waitcnt vmcnt(24)
	v_mul_f32_e32 v37, v37, v141
	v_fmac_f32_e32 v37, v36, v137
	v_mul_f32_e32 v36, v39, v134
	v_fmac_f32_e32 v36, v38, v136
	v_add_f32_e32 v36, v37, v36
	s_waitcnt vmcnt(23)
	v_mul_f32_e32 v33, v33, v141
	v_fmac_f32_e32 v33, v32, v137
	v_mul_f32_e32 v32, v35, v134
	v_fmac_f32_e32 v32, v34, v136
	v_add_f32_e32 v32, v33, v32
	s_waitcnt vmcnt(22)
	v_mul_f32_e32 v29, v29, v141
	v_fmac_f32_e32 v29, v28, v137
	v_mul_f32_e32 v28, v31, v134
	v_fmac_f32_e32 v28, v30, v136
	v_add_f32_e32 v28, v29, v28
	s_waitcnt vmcnt(21)
	v_mul_f32_e32 v25, v25, v141
	v_fmac_f32_e32 v25, v24, v137
	v_mul_f32_e32 v24, v27, v134
	v_fmac_f32_e32 v24, v26, v136
	v_add_f32_e32 v24, v25, v24
	s_waitcnt vmcnt(20)
	v_mul_f32_e32 v21, v21, v141
	v_fmac_f32_e32 v21, v20, v137
	v_mul_f32_e32 v20, v23, v134
	v_fmac_f32_e32 v20, v22, v136
	v_add_f32_e32 v20, v21, v20
	s_waitcnt vmcnt(19)
	v_mul_f32_e32 v17, v17, v141
	v_fmac_f32_e32 v17, v16, v137
	v_mul_f32_e32 v16, v19, v134
	v_fmac_f32_e32 v16, v18, v136
	v_add_f32_e32 v16, v17, v16
	s_waitcnt vmcnt(18)
	v_mul_f32_e32 v13, v13, v141
	v_fmac_f32_e32 v13, v12, v137
	v_mul_f32_e32 v12, v15, v134
	v_fmac_f32_e32 v12, v14, v136
	v_add_f32_e32 v12, v13, v12
	s_waitcnt vmcnt(17)
	v_mul_f32_e32 v9, v9, v141
	v_fmac_f32_e32 v9, v8, v137
	v_mul_f32_e32 v8, v11, v134
	v_fmac_f32_e32 v8, v10, v136
	v_add_f32_e32 v8, v9, v8
	s_waitcnt vmcnt(16)
	v_mul_f32_e32 v5, v5, v141
	v_fmac_f32_e32 v5, v4, v137
	v_mul_f32_e32 v4, v7, v134
	v_fmac_f32_e32 v4, v6, v136
	v_add_f32_e32 v4, v5, v4
	ds_bpermute_b32 v81, v205, v80
	ds_bpermute_b32 v77, v205, v76
	ds_bpermute_b32 v69, v205, v68
	ds_bpermute_b32 v61, v205, v60
	ds_bpermute_b32 v57, v205, v56
	ds_bpermute_b32 v49, v205, v48
	ds_bpermute_b32 v45, v205, v44
	ds_bpermute_b32 v37, v205, v36
	ds_bpermute_b32 v33, v205, v32
	ds_bpermute_b32 v29, v205, v28
	ds_bpermute_b32 v25, v205, v24
	ds_bpermute_b32 v21, v205, v20
	ds_bpermute_b32 v17, v205, v16
	ds_bpermute_b32 v13, v205, v12
	ds_bpermute_b32 v9, v205, v8
	ds_bpermute_b32 v5, v205, v4
	s_waitcnt lgkmcnt(0)
	v_add_f32_e32 v80, v80, v81
	v_add_f32_e32 v76, v76, v77
	v_add_f32_e32 v68, v68, v69
	v_add_f32_e32 v60, v60, v61
	v_add_f32_e32 v56, v56, v57
	v_add_f32_e32 v48, v48, v49
	v_add_f32_e32 v44, v44, v45
	v_add_f32_e32 v36, v36, v37
	v_add_f32_e32 v32, v32, v33
	v_add_f32_e32 v28, v28, v29
	v_add_f32_e32 v24, v24, v25
	v_add_f32_e32 v20, v20, v21
	v_add_f32_e32 v16, v16, v17
	v_add_f32_e32 v12, v12, v13
	v_add_f32_e32 v8, v8, v9
	v_add_f32_e32 v4, v4, v5
	ds_bpermute_b32 v81, v206, v80
	ds_bpermute_b32 v77, v206, v76
	ds_bpermute_b32 v69, v206, v68
	ds_bpermute_b32 v61, v206, v60
	ds_bpermute_b32 v57, v206, v56
	ds_bpermute_b32 v49, v206, v48
	ds_bpermute_b32 v45, v206, v44
	ds_bpermute_b32 v37, v206, v36
	ds_bpermute_b32 v33, v206, v32
	ds_bpermute_b32 v29, v206, v28
	ds_bpermute_b32 v25, v206, v24
	ds_bpermute_b32 v21, v206, v20
	ds_bpermute_b32 v17, v206, v16
	ds_bpermute_b32 v13, v206, v12
	ds_bpermute_b32 v9, v206, v8
	ds_bpermute_b32 v5, v206, v4
	s_waitcnt lgkmcnt(0)
	v_add_f32_e32 v80, v80, v81
	v_add_f32_e32 v76, v76, v77
	v_add_f32_e32 v68, v68, v69
	v_add_f32_e32 v60, v60, v61
	v_add_f32_e32 v56, v56, v57
	v_add_f32_e32 v48, v48, v49
	v_add_f32_e32 v44, v44, v45
	v_add_f32_e32 v36, v36, v37
	v_add_f32_e32 v32, v32, v33
	v_add_f32_e32 v28, v28, v29
	v_add_f32_e32 v24, v24, v25
	v_add_f32_e32 v20, v20, v21
	v_add_f32_e32 v16, v16, v17
	v_add_f32_e32 v12, v12, v13
	v_add_f32_e32 v8, v8, v9
	v_add_f32_e32 v4, v4, v5
	ds_bpermute_b32 v81, v207, v80
	ds_bpermute_b32 v77, v207, v76
	ds_bpermute_b32 v69, v207, v68
	ds_bpermute_b32 v61, v207, v60
	ds_bpermute_b32 v57, v207, v56
	ds_bpermute_b32 v49, v207, v48
	ds_bpermute_b32 v45, v207, v44
	ds_bpermute_b32 v37, v207, v36
	ds_bpermute_b32 v33, v207, v32
	ds_bpermute_b32 v29, v207, v28
	ds_bpermute_b32 v25, v207, v24
	ds_bpermute_b32 v21, v207, v20
	ds_bpermute_b32 v17, v207, v16
	ds_bpermute_b32 v13, v207, v12
	ds_bpermute_b32 v9, v207, v8
	ds_bpermute_b32 v5, v207, v4
	s_waitcnt lgkmcnt(0)
	v_add_f32_e32 v80, v80, v81
	v_add_f32_e32 v76, v76, v77
	v_add_f32_e32 v68, v68, v69
	v_add_f32_e32 v60, v60, v61
	v_add_f32_e32 v56, v56, v57
	v_add_f32_e32 v48, v48, v49
	v_add_f32_e32 v44, v44, v45
	v_add_f32_e32 v36, v36, v37
	v_add_f32_e32 v32, v32, v33
	v_add_f32_e32 v28, v28, v29
	v_add_f32_e32 v24, v24, v25
	v_add_f32_e32 v20, v20, v21
	v_add_f32_e32 v16, v16, v17
	v_add_f32_e32 v12, v12, v13
	v_add_f32_e32 v8, v8, v9
	v_add_f32_e32 v4, v4, v5
	ds_bpermute_b32 v81, v208, v80
	ds_bpermute_b32 v77, v208, v76
	ds_bpermute_b32 v69, v208, v68
	ds_bpermute_b32 v61, v208, v60
	ds_bpermute_b32 v57, v208, v56
	ds_bpermute_b32 v49, v208, v48
	ds_bpermute_b32 v45, v208, v44
	ds_bpermute_b32 v37, v208, v36
	ds_bpermute_b32 v33, v208, v32
	ds_bpermute_b32 v29, v208, v28
	ds_bpermute_b32 v25, v208, v24
	ds_bpermute_b32 v21, v208, v20
	ds_bpermute_b32 v17, v208, v16
	ds_bpermute_b32 v13, v208, v12
	ds_bpermute_b32 v9, v208, v8
	ds_bpermute_b32 v5, v208, v4
	s_waitcnt lgkmcnt(0)
	v_add_f32_e32 v80, v80, v81
	v_add_f32_e32 v76, v76, v77
	v_add_f32_e32 v68, v68, v69
	v_add_f32_e32 v60, v60, v61
	v_add_f32_e32 v56, v56, v57
	v_add_f32_e32 v48, v48, v49
	v_add_f32_e32 v44, v44, v45
	v_add_f32_e32 v36, v36, v37
	v_add_f32_e32 v32, v32, v33
	v_add_f32_e32 v28, v28, v29
	v_add_f32_e32 v24, v24, v25
	v_add_f32_e32 v20, v20, v21
	v_add_f32_e32 v16, v16, v17
	v_add_f32_e32 v12, v12, v13
	v_add_f32_e32 v8, v8, v9
	v_add_f32_e32 v4, v4, v5
	ds_bpermute_b32 v81, v209, v80
	ds_bpermute_b32 v77, v209, v76
	ds_bpermute_b32 v69, v209, v68
	ds_bpermute_b32 v61, v209, v60
	ds_bpermute_b32 v57, v209, v56
	ds_bpermute_b32 v49, v209, v48
	ds_bpermute_b32 v45, v209, v44
	ds_bpermute_b32 v37, v209, v36
	ds_bpermute_b32 v33, v209, v32
	ds_bpermute_b32 v29, v209, v28
	ds_bpermute_b32 v25, v209, v24
	ds_bpermute_b32 v21, v209, v20
	ds_bpermute_b32 v17, v209, v16
	ds_bpermute_b32 v13, v209, v12
	ds_bpermute_b32 v9, v209, v8
	ds_bpermute_b32 v5, v209, v4
	s_waitcnt lgkmcnt(0)
	v_add_f32_e32 v80, v80, v81
	v_add_f32_e32 v76, v76, v77
	v_add_f32_e32 v68, v68, v69
	v_add_f32_e32 v60, v60, v61
	v_add_f32_e32 v56, v56, v57
	v_add_f32_e32 v48, v48, v49
	v_add_f32_e32 v44, v44, v45
	v_add_f32_e32 v36, v36, v37
	v_add_f32_e32 v32, v32, v33
	v_add_f32_e32 v28, v28, v29
	v_add_f32_e32 v24, v24, v25
	v_add_f32_e32 v20, v20, v21
	v_add_f32_e32 v16, v16, v17
	v_add_f32_e32 v12, v12, v13
	v_add_f32_e32 v8, v8, v9
	v_add_f32_e32 v4, v4, v5
	s_and_saveexec_b64 s[46:47], s[40:41]
	s_cbranch_execz .Lmy_sc_lb
	ds_write_b32 v138, v80 offset:1024
	ds_write_b32 v138, v76 offset:1032
	ds_write_b32 v138, v68 offset:1040
	ds_write_b32 v138, v60 offset:1048
	ds_write_b32 v138, v56 offset:1056
	ds_write_b32 v138, v48 offset:1064
	ds_write_b32 v138, v44 offset:1072
	ds_write_b32 v138, v36 offset:1080
	ds_write_b32 v138, v32 offset:1088
	ds_write_b32 v138, v28 offset:1096
	ds_write_b32 v138, v24 offset:1104
	ds_write_b32 v138, v20 offset:1112
	ds_write_b32 v138, v16 offset:1120
	ds_write_b32 v138, v12 offset:1128
	ds_write_b32 v138, v8 offset:1136
	ds_write_b32 v138, v4 offset:1144
